# EpiResid: second half (rows +128) of the residual tile is touched by 8 dword loads issued with the first-half loads, so its dwordx4 loads after the row-statistics exchange hit in L2
# speedup vs baseline: 1.0017x; 1.0017x over previous
.LBB0_1089:
	s_or_b64 exec, exec, s[30:31]
	v_add_u32_e32 v202, s44, v216
	v_ashrrev_i32_e32 v203, 31, v202
	v_lshl_add_u64 v[200:201], v[196:197], 1, s[46:47]
	s_waitcnt lgkmcnt(0)
	v_lshlrev_b64 v[94:95], 11, v[202:203]
	v_lshl_add_u64 v[204:205], v[200:201], 0, v[94:95]
	v_or_b32_e32 v94, 16, v202
	v_ashrrev_i32_e32 v95, 31, v94
	v_lshlrev_b64 v[94:95], 11, v[94:95]
	v_lshl_add_u64 v[94:95], v[200:201], 0, v[94:95]
	s_mov_b64 s[100:101], 0x40000
	global_load_dwordx4 v[178:181], v[204:205], off
	global_load_dwordx4 v[174:177], v[204:205], off offset:256
	v_lshl_add_u64 v[248:249], v[204:205], 0, s[100:101]
	global_load_dword v250, v[248:249], off
	global_load_dword v251, v[248:249], off offset:256
	global_load_dwordx4 v[170:173], v[94:95], off
	global_load_dwordx4 v[166:169], v[94:95], off offset:256
	v_lshl_add_u64 v[248:249], v[94:95], 0, s[100:101]
	global_load_dword v252, v[248:249], off
	global_load_dword v253, v[248:249], off offset:256
	v_or_b32_e32 v94, 32, v202
	v_ashrrev_i32_e32 v95, 31, v94
	v_lshlrev_b64 v[94:95], 11, v[94:95]
	v_lshl_add_u64 v[94:95], v[200:201], 0, v[94:95]
	global_load_dwordx4 v[162:165], v[94:95], off
	global_load_dwordx4 v[158:161], v[94:95], off offset:256
	v_lshl_add_u64 v[248:249], v[94:95], 0, s[100:101]
	global_load_dword v183, v[248:249], off
	global_load_dword v189, v[248:249], off offset:256
	v_or_b32_e32 v94, 48, v202
	s_add_u32 s10, s10, s80
	v_ashrrev_i32_e32 v95, 31, v94
	s_addc_u32 s11, s11, 0
	v_lshlrev_b64 v[94:95], 11, v[94:95]
	v_lshl_add_u64 v[94:95], v[200:201], 0, v[94:95]
	v_lshl_add_u64 v[102:103], v[196:197], 2, s[10:11]
	global_load_dwordx4 v[154:157], v[94:95], off
	global_load_dwordx4 v[150:153], v[94:95], off offset:256
	v_lshl_add_u64 v[248:249], v[94:95], 0, s[100:101]
	global_load_dword v191, v[248:249], off
	global_load_dword v193, v[248:249], off offset:256
	global_load_dwordx4 v[110:113], v[102:103], off offset:16
	global_load_dwordx4 v[114:117], v[102:103], off
	s_nop 0
	global_load_dwordx4 v[94:97], v[102:103], off offset:528
	s_nop 0
	global_load_dwordx4 v[102:105], v[102:103], off offset:512
	s_and_saveexec_b64 s[30:31], s[6:7]
	s_cbranch_execz .LBB0_1100
	v_lshlrev_b64 v[206:207], 5, v[198:199]
	v_lshl_add_u64 v[210:211], s[52:53], 0, v[206:207]
	s_mov_b32 s15, 0
	s_branch .LBB0_1093
